# seam1: L1 invalidate issued right after the group-barrier arrival atomic (overlaps the wait) instead of after release is seen
# baseline (speedup 1.0000x reference)
.LBB0_462:
	s_lshl_b32 s0, s4, 8
	s_add_u32 s36, s44, s0
	s_addc_u32 s4, s45, 0
	v_mov_b32_e32 v3, s36
	v_add_co_u32_e32 v4, vcc, 0x1000, v3
	v_mov_b32_e32 v3, s4
	s_nop 0
	v_addc_co_u32_e32 v5, vcc, 0, v3, vcc
	flat_atomic_add v4, v[4:5], v200 offset:1024 sc0
	buffer_inv sc1
	v_cvt_f32_u32_e32 v3, v2
	v_sub_u32_e32 v5, 0, v2
	v_rcp_iflag_f32_e32 v3, v3
	s_nop 0
	v_mul_f32_e32 v3, 0x4f7ffffe, v3
	v_cvt_u32_f32_e32 v3, v3
	v_mul_lo_u32 v5, v5, v3
	v_mul_hi_u32 v5, v3, v5
	v_add_u32_e32 v3, v3, v5
	s_waitcnt vmcnt(1) lgkmcnt(0)
	v_mul_hi_u32 v3, v4, v3
	v_mul_lo_u32 v5, v3, v2
	v_sub_u32_e32 v5, v4, v5
	v_cmp_ge_u32_e32 vcc, v5, v2
	v_add_u32_e32 v6, 1, v3
	s_nop 0
	v_cndmask_b32_e32 v3, v3, v6, vcc
	v_sub_u32_e32 v6, v5, v2
	v_cndmask_b32_e32 v5, v5, v6, vcc
	v_cmp_ge_u32_e32 vcc, v5, v2
	v_add_u32_e32 v5, 1, v3
	v_add_u32_e32 v6, 1, v4
	v_cndmask_b32_e32 v3, v3, v5, vcc
	v_mad_u64_u32 v[4:5], s[0:1], v2, v3, v[2:3]
	v_cmp_ne_u32_e32 vcc, v6, v4
	s_and_saveexec_b64 s[0:1], vcc
	s_xor_b64 s[0:1], exec, s[0:1]
	s_cbranch_execz .LBB0_475
	v_mov_b32_e32 v0, s36
	v_add_co_u32_e32 v4, vcc, 0x2000, v0
	v_mov_b32_e32 v0, s4
	s_nop 0
	v_addc_co_u32_e32 v5, vcc, 0, v0, vcc
	flat_load_dword v0, v[4:5] offset:1024 sc1
	s_add_u32 s16, s36, 0x2400
	s_addc_u32 s17, s4, 0
	s_waitcnt vmcnt(0) lgkmcnt(0)
	v_cmp_eq_u32_e32 vcc, v0, v3
	s_and_saveexec_b64 s[14:15], vcc
	s_cbranch_execz .LBB0_474
	s_mov_b32 s34, 1
	s_mov_b64 s[18:19], 0
	s_branch .LBB0_466

.LBB0_474:
	s_or_b64 exec, exec, s[14:15]
	s_waitcnt vmcnt(0) lgkmcnt(0)
	s_waitcnt vmcnt(0)
.LBB0_475:
	s_andn2_saveexec_b64 s[0:1], s[0:1]
	s_cbranch_execz .LBB0_494
	v_cmp_lt_u32_e32 vcc, 1, v0
	s_and_saveexec_b64 s[0:1], vcc
	s_cbranch_execz .LBB0_478
	buffer_wbl2 sc1
	s_waitcnt vmcnt(0)
.LBB0_478:
	s_or_b64 exec, exec, s[0:1]
	s_and_saveexec_b64 s[0:1], vcc
	s_cbranch_execz .LBB0_493
	v_mov_b32_e32 v2, s44
	v_add_co_u32_e32 v2, vcc, 0x3000, v2
	v_mov_b32_e32 v3, s45
	s_nop 0
	v_addc_co_u32_e32 v3, vcc, 0, v3, vcc
	flat_atomic_add v2, v[2:3], v200 offset:1024 sc0
	v_cvt_f32_u32_e32 v3, v0
	v_sub_u32_e32 v4, 0, v0
	s_mov_b64 s[18:19], -1
	v_rcp_iflag_f32_e32 v3, v3
	s_nop 0
	v_mul_f32_e32 v3, 0x4f7ffffe, v3
	v_cvt_u32_f32_e32 v3, v3
	v_mul_lo_u32 v4, v4, v3
	v_mul_hi_u32 v4, v3, v4
	v_add_u32_e32 v3, v3, v4
	s_waitcnt vmcnt(0) lgkmcnt(0)
	v_mul_hi_u32 v3, v2, v3
	v_mul_lo_u32 v4, v3, v0
	v_sub_u32_e32 v4, v2, v4
	v_cmp_ge_u32_e32 vcc, v4, v0
	v_add_u32_e32 v5, 1, v3
	s_nop 0
	v_cndmask_b32_e32 v3, v3, v5, vcc
	v_sub_u32_e32 v5, v4, v0
	v_cndmask_b32_e32 v4, v4, v5, vcc
	v_cmp_ge_u32_e32 vcc, v4, v0
	v_add_u32_e32 v4, 1, v3
	v_add_u32_e32 v5, 1, v2
	v_cndmask_b32_e32 v4, v3, v4, vcc
	v_mad_u64_u32 v[2:3], s[14:15], v0, v4, v[0:1]
	s_add_u32 s14, s44, 0x3500
	s_addc_u32 s15, s45, 0
	v_cmp_ne_u32_e32 vcc, v5, v2
	v_mov_b64_e32 v[2:3], s[14:15]
	s_and_saveexec_b64 s[16:17], vcc
	s_cbranch_execz .LBB0_491
	v_mov_b64_e32 v[2:3], s[14:15]
	flat_load_dword v0, v[2:3] sc1
	s_mov_b64 s[22:23], 0
	s_waitcnt vmcnt(0) lgkmcnt(0)
	v_cmp_eq_u32_e32 vcc, v0, v4
	s_and_saveexec_b64 s[20:21], vcc
	s_cbranch_execz .LBB0_490
	s_add_u32 s18, s44, 0x200
	s_addc_u32 s19, s45, 0
	s_mov_b32 s37, 1
	s_branch .LBB0_483

.LBB0_493:
	s_or_b64 exec, exec, s[0:1]
	v_mov_b32_e32 v0, s36
	v_add_co_u32_e32 v2, vcc, 0x2000, v0
	v_mov_b32_e32 v0, s4
	s_nop 0
	v_addc_co_u32_e32 v3, vcc, 0, v0, vcc
	s_waitcnt lgkmcnt(0)
	flat_atomic_add v[2:3], v200 offset:1024
	s_waitcnt vmcnt(0)

.LBB0_642:
	s_lshl_b32 s0, s4, 8
	s_add_u32 s36, s14, s0
	s_addc_u32 s4, s15, 0
	v_mov_b32_e32 v3, s36
	v_add_co_u32_e32 v4, vcc, 0x1000, v3
	v_mov_b32_e32 v3, s4
	s_nop 0
	v_addc_co_u32_e32 v5, vcc, 0, v3, vcc
	flat_atomic_add v4, v[4:5], v200 offset:1024 sc0
	buffer_inv sc1
	v_cvt_f32_u32_e32 v3, v2
	v_sub_u32_e32 v5, 0, v2
	v_rcp_iflag_f32_e32 v3, v3
	s_nop 0
	v_mul_f32_e32 v3, 0x4f7ffffe, v3
	v_cvt_u32_f32_e32 v3, v3
	v_mul_lo_u32 v5, v5, v3
	v_mul_hi_u32 v5, v3, v5
	v_add_u32_e32 v3, v3, v5
	s_waitcnt vmcnt(1) lgkmcnt(0)
	v_mul_hi_u32 v3, v4, v3
	v_mul_lo_u32 v5, v3, v2
	v_sub_u32_e32 v5, v4, v5
	v_cmp_ge_u32_e32 vcc, v5, v2
	v_add_u32_e32 v6, 1, v3
	s_nop 0
	v_cndmask_b32_e32 v3, v3, v6, vcc
	v_sub_u32_e32 v6, v5, v2
	v_cndmask_b32_e32 v5, v5, v6, vcc
	v_cmp_ge_u32_e32 vcc, v5, v2
	v_add_u32_e32 v5, 1, v3
	v_add_u32_e32 v6, 1, v4
	v_cndmask_b32_e32 v3, v3, v5, vcc
	v_mad_u64_u32 v[4:5], s[0:1], v2, v3, v[2:3]
	v_cmp_ne_u32_e32 vcc, v6, v4
	s_and_saveexec_b64 s[0:1], vcc
	s_xor_b64 s[0:1], exec, s[0:1]
	s_cbranch_execz .LBB0_655
	v_mov_b32_e32 v0, s36
	v_add_co_u32_e32 v4, vcc, 0x2000, v0
	v_mov_b32_e32 v0, s4
	s_nop 0
	v_addc_co_u32_e32 v5, vcc, 0, v0, vcc
	flat_load_dword v0, v[4:5] offset:1024 sc1
	s_add_u32 s18, s36, 0x2400
	s_addc_u32 s19, s4, 0
	s_waitcnt vmcnt(0) lgkmcnt(0)
	v_cmp_eq_u32_e32 vcc, v0, v3
	s_and_saveexec_b64 s[16:17], vcc
	s_cbranch_execz .LBB0_654
	s_mov_b32 s37, 1
	s_mov_b64 s[20:21], 0
	s_branch .LBB0_646

.LBB0_654:
	s_or_b64 exec, exec, s[16:17]
	s_waitcnt vmcnt(0) lgkmcnt(0)
	s_waitcnt vmcnt(0)

.LBB0_658:
	s_or_b64 exec, exec, s[0:1]
	s_and_saveexec_b64 s[0:1], vcc
	s_cbranch_execz .LBB0_673
	v_mov_b32_e32 v2, s14
	v_add_co_u32_e32 v2, vcc, 0x3000, v2
	v_mov_b32_e32 v3, s15
	s_nop 0
	v_addc_co_u32_e32 v3, vcc, 0, v3, vcc
	flat_atomic_add v2, v[2:3], v200 offset:1024 sc0
	v_cvt_f32_u32_e32 v3, v0
	v_sub_u32_e32 v4, 0, v0
	s_mov_b64 s[20:21], -1
	v_rcp_iflag_f32_e32 v3, v3
	s_nop 0
	v_mul_f32_e32 v3, 0x4f7ffffe, v3
	v_cvt_u32_f32_e32 v3, v3
	v_mul_lo_u32 v4, v4, v3
	v_mul_hi_u32 v4, v3, v4
	v_add_u32_e32 v3, v3, v4
	s_waitcnt vmcnt(0) lgkmcnt(0)
	v_mul_hi_u32 v3, v2, v3
	v_mul_lo_u32 v4, v3, v0
	v_sub_u32_e32 v4, v2, v4
	v_cmp_ge_u32_e32 vcc, v4, v0
	v_add_u32_e32 v5, 1, v3
	s_nop 0
	v_cndmask_b32_e32 v3, v3, v5, vcc
	v_sub_u32_e32 v5, v4, v0
	v_cndmask_b32_e32 v4, v4, v5, vcc
	v_cmp_ge_u32_e32 vcc, v4, v0
	v_add_u32_e32 v4, 1, v3
	v_add_u32_e32 v5, 1, v2
	v_cndmask_b32_e32 v4, v3, v4, vcc
	v_mad_u64_u32 v[2:3], s[16:17], v0, v4, v[0:1]
	s_add_u32 s16, s14, 0x3500
	s_addc_u32 s17, s15, 0
	v_cmp_ne_u32_e32 vcc, v5, v2
	v_mov_b64_e32 v[2:3], s[16:17]
	s_and_saveexec_b64 s[18:19], vcc
	s_cbranch_execz .LBB0_671
	v_mov_b64_e32 v[2:3], s[16:17]
	flat_load_dword v0, v[2:3] sc1
	s_mov_b64 s[24:25], 0
	s_waitcnt vmcnt(0) lgkmcnt(0)
	v_cmp_eq_u32_e32 vcc, v0, v4
	s_and_saveexec_b64 s[22:23], vcc
	s_cbranch_execz .LBB0_670
	s_add_u32 s20, s14, 0x200
	s_addc_u32 s21, s15, 0
	s_mov_b32 s37, 1
	s_mov_b64 s[14:15], 0
	s_branch .LBB0_663

.LBB0_1265:
	s_lshl_b32 s0, s4, 8
	s_add_u32 s38, s46, s0
	s_addc_u32 s4, s47, 0
	v_mov_b32_e32 v3, s38
	v_add_co_u32_e32 v4, vcc, 0x1000, v3
	v_mov_b32_e32 v3, s4
	s_nop 0
	v_addc_co_u32_e32 v5, vcc, 0, v3, vcc
	flat_atomic_add v4, v[4:5], v200 offset:1024 sc0
	buffer_inv sc1
	v_cvt_f32_u32_e32 v3, v2
	v_sub_u32_e32 v5, 0, v2
	v_rcp_iflag_f32_e32 v3, v3
	s_nop 0
	v_mul_f32_e32 v3, 0x4f7ffffe, v3
	v_cvt_u32_f32_e32 v3, v3
	v_mul_lo_u32 v5, v5, v3
	v_mul_hi_u32 v5, v3, v5
	v_add_u32_e32 v3, v3, v5
	s_waitcnt vmcnt(1) lgkmcnt(0)
	v_mul_hi_u32 v3, v4, v3
	v_mul_lo_u32 v5, v3, v2
	v_sub_u32_e32 v5, v4, v5
	v_cmp_ge_u32_e32 vcc, v5, v2
	v_add_u32_e32 v6, 1, v3
	s_nop 0
	v_cndmask_b32_e32 v3, v3, v6, vcc
	v_sub_u32_e32 v6, v5, v2
	v_cndmask_b32_e32 v5, v5, v6, vcc
	v_cmp_ge_u32_e32 vcc, v5, v2
	v_add_u32_e32 v5, 1, v3
	v_add_u32_e32 v6, 1, v4
	v_cndmask_b32_e32 v3, v3, v5, vcc
	v_mad_u64_u32 v[4:5], s[0:1], v2, v3, v[2:3]
	v_cmp_ne_u32_e32 vcc, v6, v4
	s_and_saveexec_b64 s[0:1], vcc
	s_xor_b64 s[0:1], exec, s[0:1]
	s_cbranch_execz .LBB0_1278
	v_mov_b32_e32 v0, s38
	v_add_co_u32_e32 v4, vcc, 0x2000, v0
	v_mov_b32_e32 v0, s4
	s_nop 0
	v_addc_co_u32_e32 v5, vcc, 0, v0, vcc
	flat_load_dword v0, v[4:5] offset:1024 sc1
	s_add_u32 s18, s38, 0x2400
	s_addc_u32 s19, s4, 0
	s_waitcnt vmcnt(0) lgkmcnt(0)
	v_cmp_eq_u32_e32 vcc, v0, v3
	s_and_saveexec_b64 s[16:17], vcc
	s_cbranch_execz .LBB0_1277
	s_mov_b32 s36, 1
	s_mov_b64 s[20:21], 0
	s_branch .LBB0_1269

.LBB0_1281:
	s_or_b64 exec, exec, s[0:1]
	s_and_saveexec_b64 s[0:1], vcc
	s_cbranch_execz .LBB0_1296
	v_mov_b32_e32 v2, s46
	v_add_co_u32_e32 v2, vcc, 0x3000, v2
	v_mov_b32_e32 v3, s47
	s_nop 0
	v_addc_co_u32_e32 v3, vcc, 0, v3, vcc
	flat_atomic_add v2, v[2:3], v200 offset:1024 sc0
	v_cvt_f32_u32_e32 v3, v0
	v_sub_u32_e32 v4, 0, v0
	s_mov_b64 s[20:21], -1
	v_rcp_iflag_f32_e32 v3, v3
	s_nop 0
	v_mul_f32_e32 v3, 0x4f7ffffe, v3
	v_cvt_u32_f32_e32 v3, v3
	v_mul_lo_u32 v4, v4, v3
	v_mul_hi_u32 v4, v3, v4
	v_add_u32_e32 v3, v3, v4
	s_waitcnt vmcnt(0) lgkmcnt(0)
	v_mul_hi_u32 v3, v2, v3
	v_mul_lo_u32 v4, v3, v0
	v_sub_u32_e32 v4, v2, v4
	v_cmp_ge_u32_e32 vcc, v4, v0
	v_add_u32_e32 v5, 1, v3
	s_nop 0
	v_cndmask_b32_e32 v3, v3, v5, vcc
	v_sub_u32_e32 v5, v4, v0
	v_cndmask_b32_e32 v4, v4, v5, vcc
	v_cmp_ge_u32_e32 vcc, v4, v0
	v_add_u32_e32 v4, 1, v3
	v_add_u32_e32 v5, 1, v2
	v_cndmask_b32_e32 v4, v3, v4, vcc
	v_mad_u64_u32 v[2:3], s[16:17], v0, v4, v[0:1]
	s_add_u32 s16, s46, 0x3500
	s_addc_u32 s17, s47, 0
	v_cmp_ne_u32_e32 vcc, v5, v2
	v_mov_b64_e32 v[2:3], s[16:17]
	s_and_saveexec_b64 s[18:19], vcc
	s_cbranch_execz .LBB0_1294
	v_mov_b64_e32 v[2:3], s[16:17]
	flat_load_dword v0, v[2:3] sc1
	s_mov_b64 s[24:25], 0
	s_waitcnt vmcnt(0) lgkmcnt(0)
	v_cmp_eq_u32_e32 vcc, v0, v4
	s_and_saveexec_b64 s[22:23], vcc
	s_cbranch_execz .LBB0_1293
	s_add_u32 s20, s46, 0x200
	s_addc_u32 s21, s47, 0
	s_mov_b32 s39, 1
	s_branch .LBB0_1286

.LBB0_1296:
	s_or_b64 exec, exec, s[0:1]
	v_mov_b32_e32 v0, s38
	v_add_co_u32_e32 v2, vcc, 0x2000, v0
	v_mov_b32_e32 v0, s4
	s_nop 0
	v_addc_co_u32_e32 v3, vcc, 0, v0, vcc
	s_waitcnt lgkmcnt(0)
	flat_atomic_add v[2:3], v200 offset:1024
	s_waitcnt vmcnt(0)

.LBB0_1414:
	s_lshl_b32 s0, s4, 8
	s_add_u32 s36, s48, s0
	s_addc_u32 s4, s49, 0
	v_mov_b32_e32 v3, s36
	v_add_co_u32_e32 v4, vcc, 0x1000, v3
	v_mov_b32_e32 v3, s4
	s_nop 0
	v_addc_co_u32_e32 v5, vcc, 0, v3, vcc
	flat_atomic_add v4, v[4:5], v200 offset:1024 sc0
	buffer_inv sc1
	v_cvt_f32_u32_e32 v3, v2
	v_sub_u32_e32 v5, 0, v2
	v_rcp_iflag_f32_e32 v3, v3
	s_nop 0
	v_mul_f32_e32 v3, 0x4f7ffffe, v3
	v_cvt_u32_f32_e32 v3, v3
	v_mul_lo_u32 v5, v5, v3
	v_mul_hi_u32 v5, v3, v5
	v_add_u32_e32 v3, v3, v5
	s_waitcnt vmcnt(1) lgkmcnt(0)
	v_mul_hi_u32 v3, v4, v3
	v_mul_lo_u32 v5, v3, v2
	v_sub_u32_e32 v5, v4, v5
	v_cmp_ge_u32_e32 vcc, v5, v2
	v_add_u32_e32 v6, 1, v3
	s_nop 0
	v_cndmask_b32_e32 v3, v3, v6, vcc
	v_sub_u32_e32 v6, v5, v2
	v_cndmask_b32_e32 v5, v5, v6, vcc
	v_cmp_ge_u32_e32 vcc, v5, v2
	v_add_u32_e32 v5, 1, v3
	v_add_u32_e32 v6, 1, v4
	v_cndmask_b32_e32 v3, v3, v5, vcc
	v_mad_u64_u32 v[4:5], s[0:1], v2, v3, v[2:3]
	v_cmp_ne_u32_e32 vcc, v6, v4
	s_and_saveexec_b64 s[0:1], vcc
	s_xor_b64 s[0:1], exec, s[0:1]
	s_cbranch_execz .LBB0_1427
	v_mov_b32_e32 v0, s36
	v_add_co_u32_e32 v4, vcc, 0x2000, v0
	v_mov_b32_e32 v0, s4
	s_nop 0
	v_addc_co_u32_e32 v5, vcc, 0, v0, vcc
	flat_load_dword v0, v[4:5] offset:1024 sc1
	s_add_u32 s16, s36, 0x2400
	s_addc_u32 s17, s4, 0
	s_waitcnt vmcnt(0) lgkmcnt(0)
	v_cmp_eq_u32_e32 vcc, v0, v3
	s_and_saveexec_b64 s[12:13], vcc
	s_cbranch_execz .LBB0_1426
	s_mov_b32 s34, 1
	s_mov_b64 s[18:19], 0
	s_branch .LBB0_1418

.LBB0_1426:
	s_or_b64 exec, exec, s[12:13]
	s_waitcnt vmcnt(0) lgkmcnt(0)
	s_waitcnt vmcnt(0)

.LBB0_1430:
	s_or_b64 exec, exec, s[0:1]
	s_and_saveexec_b64 s[0:1], vcc
	s_cbranch_execz .LBB0_1445
	v_mov_b32_e32 v2, s48
	v_add_co_u32_e32 v2, vcc, 0x3000, v2
	v_mov_b32_e32 v3, s49
	s_nop 0
	v_addc_co_u32_e32 v3, vcc, 0, v3, vcc
	flat_atomic_add v2, v[2:3], v200 offset:1024 sc0
	v_cvt_f32_u32_e32 v3, v0
	v_sub_u32_e32 v4, 0, v0
	s_mov_b64 s[18:19], -1
	v_rcp_iflag_f32_e32 v3, v3
	s_nop 0
	v_mul_f32_e32 v3, 0x4f7ffffe, v3
	v_cvt_u32_f32_e32 v3, v3
	v_mul_lo_u32 v4, v4, v3
	v_mul_hi_u32 v4, v3, v4
	v_add_u32_e32 v3, v3, v4
	s_waitcnt vmcnt(0) lgkmcnt(0)
	v_mul_hi_u32 v3, v2, v3
	v_mul_lo_u32 v4, v3, v0
	v_sub_u32_e32 v4, v2, v4
	v_cmp_ge_u32_e32 vcc, v4, v0
	v_add_u32_e32 v5, 1, v3
	s_nop 0
	v_cndmask_b32_e32 v3, v3, v5, vcc
	v_sub_u32_e32 v5, v4, v0
	v_cndmask_b32_e32 v4, v4, v5, vcc
	v_cmp_ge_u32_e32 vcc, v4, v0
	v_add_u32_e32 v4, 1, v3
	v_add_u32_e32 v5, 1, v2
	v_cndmask_b32_e32 v4, v3, v4, vcc
	v_mad_u64_u32 v[2:3], s[12:13], v0, v4, v[0:1]
	s_add_u32 s12, s48, 0x3500
	s_addc_u32 s13, s49, 0
	v_cmp_ne_u32_e32 vcc, v5, v2
	v_mov_b64_e32 v[2:3], s[12:13]
	s_and_saveexec_b64 s[16:17], vcc
	s_cbranch_execz .LBB0_1443
	v_mov_b64_e32 v[2:3], s[12:13]
	flat_load_dword v0, v[2:3] sc1
	s_mov_b64 s[22:23], 0
	s_waitcnt vmcnt(0) lgkmcnt(0)
	v_cmp_eq_u32_e32 vcc, v0, v4
	s_and_saveexec_b64 s[20:21], vcc
	s_cbranch_execz .LBB0_1442
	s_add_u32 s18, s48, 0x200
	s_addc_u32 s19, s49, 0
	s_mov_b32 s37, 1
	s_branch .LBB0_1435

.LBB0_1589:
	s_lshl_b32 s0, s4, 8
	s_add_u32 s34, s44, s0
	s_addc_u32 s4, s45, 0
	v_mov_b32_e32 v3, s34
	v_add_co_u32_e32 v4, vcc, 0x1000, v3
	v_mov_b32_e32 v3, s4
	s_nop 0
	v_addc_co_u32_e32 v5, vcc, 0, v3, vcc
	flat_atomic_add v4, v[4:5], v200 offset:1024 sc0
	buffer_inv sc1
	v_cvt_f32_u32_e32 v3, v2
	v_sub_u32_e32 v5, 0, v2
	v_rcp_iflag_f32_e32 v3, v3
	s_nop 0
	v_mul_f32_e32 v3, 0x4f7ffffe, v3
	v_cvt_u32_f32_e32 v3, v3
	v_mul_lo_u32 v5, v5, v3
	v_mul_hi_u32 v5, v3, v5
	v_add_u32_e32 v3, v3, v5
	s_waitcnt vmcnt(1) lgkmcnt(0)
	v_mul_hi_u32 v3, v4, v3
	v_mul_lo_u32 v5, v3, v2
	v_sub_u32_e32 v5, v4, v5
	v_cmp_ge_u32_e32 vcc, v5, v2
	v_add_u32_e32 v6, 1, v3
	s_nop 0
	v_cndmask_b32_e32 v3, v3, v6, vcc
	v_sub_u32_e32 v6, v5, v2
	v_cndmask_b32_e32 v5, v5, v6, vcc
	v_cmp_ge_u32_e32 vcc, v5, v2
	v_add_u32_e32 v5, 1, v3
	v_add_u32_e32 v6, 1, v4
	v_cndmask_b32_e32 v3, v3, v5, vcc
	v_mad_u64_u32 v[4:5], s[0:1], v2, v3, v[2:3]
	v_cmp_ne_u32_e32 vcc, v6, v4
	s_and_saveexec_b64 s[0:1], vcc
	s_xor_b64 s[0:1], exec, s[0:1]
	s_cbranch_execz .LBB0_1602
	v_mov_b32_e32 v0, s34
	v_add_co_u32_e32 v4, vcc, 0x2000, v0
	v_mov_b32_e32 v0, s4
	s_nop 0
	v_addc_co_u32_e32 v5, vcc, 0, v0, vcc
	flat_load_dword v0, v[4:5] offset:1024 sc1
	s_add_u32 s14, s34, 0x2400
	s_addc_u32 s15, s4, 0
	s_waitcnt vmcnt(0) lgkmcnt(0)
	v_cmp_eq_u32_e32 vcc, v0, v3
	s_and_saveexec_b64 s[12:13], vcc
	s_cbranch_execz .LBB0_1601
	s_mov_b32 s30, 1
	s_mov_b64 s[16:17], 0
	s_branch .LBB0_1593

.LBB0_1605:
	s_or_b64 exec, exec, s[0:1]
	s_and_saveexec_b64 s[0:1], vcc
	s_cbranch_execz .LBB0_1620
	v_mov_b32_e32 v2, s44
	v_add_co_u32_e32 v2, vcc, 0x3000, v2
	v_mov_b32_e32 v3, s45
	s_nop 0
	v_addc_co_u32_e32 v3, vcc, 0, v3, vcc
	flat_atomic_add v2, v[2:3], v200 offset:1024 sc0
	v_cvt_f32_u32_e32 v3, v0
	v_sub_u32_e32 v4, 0, v0
	s_mov_b64 s[16:17], -1
	v_rcp_iflag_f32_e32 v3, v3
	s_nop 0
	v_mul_f32_e32 v3, 0x4f7ffffe, v3
	v_cvt_u32_f32_e32 v3, v3
	v_mul_lo_u32 v4, v4, v3
	v_mul_hi_u32 v4, v3, v4
	v_add_u32_e32 v3, v3, v4
	s_waitcnt vmcnt(0) lgkmcnt(0)
	v_mul_hi_u32 v3, v2, v3
	v_mul_lo_u32 v4, v3, v0
	v_sub_u32_e32 v4, v2, v4
	v_cmp_ge_u32_e32 vcc, v4, v0
	v_add_u32_e32 v5, 1, v3
	s_nop 0
	v_cndmask_b32_e32 v3, v3, v5, vcc
	v_sub_u32_e32 v5, v4, v0
	v_cndmask_b32_e32 v4, v4, v5, vcc
	v_cmp_ge_u32_e32 vcc, v4, v0
	v_add_u32_e32 v4, 1, v3
	v_add_u32_e32 v5, 1, v2
	v_cndmask_b32_e32 v4, v3, v4, vcc
	v_mad_u64_u32 v[2:3], s[12:13], v0, v4, v[0:1]
	s_add_u32 s12, s44, 0x3500
	s_addc_u32 s13, s45, 0
	v_cmp_ne_u32_e32 vcc, v5, v2
	v_mov_b64_e32 v[2:3], s[12:13]
	s_and_saveexec_b64 s[14:15], vcc
	s_cbranch_execz .LBB0_1618
	v_mov_b64_e32 v[2:3], s[12:13]
	flat_load_dword v0, v[2:3] sc1
	s_mov_b64 s[20:21], 0
	s_waitcnt vmcnt(0) lgkmcnt(0)
	v_cmp_eq_u32_e32 vcc, v0, v4
	s_and_saveexec_b64 s[18:19], vcc
	s_cbranch_execz .LBB0_1617
	s_add_u32 s16, s44, 0x200
	s_addc_u32 s17, s45, 0
	s_mov_b32 s35, 1
	s_branch .LBB0_1610

.LBB0_1620:
	s_or_b64 exec, exec, s[0:1]
	v_mov_b32_e32 v0, s34
	v_add_co_u32_e32 v2, vcc, 0x2000, v0
	v_mov_b32_e32 v0, s4
	s_nop 0
	v_addc_co_u32_e32 v3, vcc, 0, v0, vcc
	s_waitcnt lgkmcnt(0)
	flat_atomic_add v[2:3], v200 offset:1024
	s_waitcnt vmcnt(0)
